# v60 plus nt stores for the write-only f32 cache outputs of the in-proj epilogue
# speedup vs baseline: 1.0211x; 1.0003x over previous
.LBB0_495:
	v_lshrrev_b32_e32 v159, 1, v159
	v_and_b32_e32 v169, 12, v159
	v_lshrrev_b32_e32 v159, 1, v158
	v_mov_b64_e32 v[174:175], s[10:11]
	v_and_b32_e32 v164, 0xffffffc0, v158
	v_and_b32_e32 v181, 28, v159
	v_mad_i64_i32 v[174:175], s[6:7], v168, s93, v[174:175]
	v_cndmask_b32_e64 v159, 0, 1, s[34:35]
	v_ashrrev_i32_e32 v165, 31, v164
	v_cvt_pk_bf16_f32 v184, v142, v143
	v_cvt_pk_bf16_f32 v185, v144, v145
	v_cvt_pk_bf16_f32 v186, v138, v139
	v_cvt_pk_bf16_f32 v187, v140, v141
	v_lshl_add_u64 v[174:175], v[160:161], 1, v[174:175]
	v_cmp_ne_u32_e64 s[6:7], 1, v159
	s_andn2_b64 vcc, exec, s[34:35]
	flat_store_dwordx4 v[174:175], v[184:187]
	s_cbranch_vccnz .LBB0_506
	s_lshl_b32 s25, s12, 2
	s_add_i32 s34, s25, s74
	s_ashr_i32 s35, s34, 31
	s_mov_b64 s[66:67], -1
	s_mov_b64 s[56:57], 0
	s_cmp_lt_i32 s0, 9
	s_mov_b64 s[76:77], 0
	s_cbranch_scc1 .LBB0_502
	s_cmp_eq_u32 s0, 9
	s_mov_b64 s[76:77], -1
	s_cbranch_scc0 .LBB0_499
	s_lshl_b64 s[66:67], s[34:35], 18
	v_ashrrev_i32_e32 v171, 31, v170
	s_add_u32 s66, s48, s66
	s_addc_u32 s67, s49, s67
	v_lshlrev_b64 v[184:185], 10, v[170:171]
	v_and_b32_e32 v186, 0xffffffe0, v158
	v_lshl_add_u64 v[184:185], s[66:67], 0, v[184:185]
	v_ashrrev_i32_e32 v187, 31, v186
	v_lshl_add_u64 v[184:185], v[186:187], 2, v[184:185]
	v_lshlrev_b32_e32 v186, 2, v169
	v_mov_b32_e32 v187, v65
	v_lshl_add_u64 v[188:189], v[184:185], 0, v[186:187]
	v_mov_b32_e32 v184, v142
	v_mov_b32_e32 v185, v144
	v_mov_b32_e32 v186, v138
	v_mov_b32_e32 v187, v140
	global_store_dwordx4 v[188:189], v[184:187], off nt
	s_mov_b64 s[76:77], 0
	s_nop 0
	v_mov_b32_e32 v184, v143
	v_mov_b32_e32 v185, v145
	v_mov_b32_e32 v186, v139
	v_mov_b32_e32 v187, v141
	global_store_dwordx4 v[188:189], v[184:187], off offset:64 nt

.LBB0_501:
	s_lshl_b64 s[56:57], s[34:35], 18
	s_add_u32 s56, s69, s56
	v_ashrrev_i32_e32 v171, 31, v170
	s_addc_u32 s57, s62, s57
	v_lshlrev_b64 v[184:185], 10, v[170:171]
	v_lshl_add_u64 v[184:185], s[56:57], 0, v[184:185]
	v_ashrrev_i32_e32 v159, 31, v158
	v_lshl_add_u64 v[184:185], v[158:159], 2, v[184:185]
	global_store_dwordx4 v[184:185], v[142:145], off nt
	global_store_dwordx4 v[184:185], v[138:141], off offset:16 nt
	s_cbranch_execz .LBB0_505
	s_branch .LBB0_506

.LBB0_505:
	s_lshl_b64 s[34:35], s[34:35], 17
	v_ashrrev_i32_e32 v171, 31, v170
	s_add_u32 s34, s50, s34
	s_addc_u32 s35, s68, s35
	v_lshlrev_b64 v[184:185], 9, v[170:171]
	v_lshl_add_u64 v[184:185], s[34:35], 0, v[184:185]
	v_lshl_add_u64 v[184:185], v[164:165], 2, v[184:185]
	v_lshlrev_b32_e32 v186, 2, v181
	v_mov_b32_e32 v187, v65
	v_lshl_add_u64 v[188:189], v[184:185], 0, v[186:187]
	v_mov_b32_e32 v184, v142
	v_mov_b32_e32 v185, v144
	v_mov_b32_e32 v186, v138
	v_mov_b32_e32 v187, v140
	v_mov_b32_e32 v142, v143
	v_mov_b32_e32 v143, v145
	v_mov_b32_e32 v144, v139
	v_mov_b32_e32 v145, v141
	global_store_dwordx4 v[188:189], v[184:187], off nt
	global_store_dwordx4 v[188:189], v[142:145], off offset:128 nt

.LBB0_514:
	v_add_u32_e32 v140, 0x80, v158
	v_cvt_pk_bf16_f32 v142, v134, v135
	v_cvt_pk_bf16_f32 v143, v136, v137
	v_cvt_pk_bf16_f32 v144, v130, v131
	v_cvt_pk_bf16_f32 v145, v132, v133
	s_and_b64 vcc, exec, s[6:7]
	flat_store_dwordx4 v[174:175], v[142:145] offset:256
	s_cbranch_vccnz .LBB0_523
	s_lshl_b32 s25, s12, 2
	s_add_i32 s34, s25, s74
	s_ashr_i32 s35, s34, 31
	v_ashrrev_i32_e32 v171, 31, v170
	s_mov_b64 s[66:67], -1
	s_mov_b64 s[56:57], 0
	s_cmp_lt_i32 s0, 9
	s_mov_b64 s[76:77], 0
	s_cbranch_scc1 .LBB0_525
	s_cmp_eq_u32 s0, 9
	s_mov_b64 s[76:77], -1
	s_cbranch_scc0 .LBB0_518
	s_lshl_b64 s[66:67], s[34:35], 18
	s_add_u32 s66, s48, s66
	s_addc_u32 s67, s49, s67
	v_lshlrev_b64 v[138:139], 10, v[170:171]
	v_and_b32_e32 v142, 0xffffffe0, v140
	v_lshl_add_u64 v[138:139], s[66:67], 0, v[138:139]
	v_ashrrev_i32_e32 v143, 31, v142
	v_lshl_add_u64 v[138:139], v[142:143], 2, v[138:139]
	v_lshlrev_b32_e32 v64, 2, v169
	v_lshl_add_u64 v[138:139], v[138:139], 0, v[64:65]
	v_mov_b32_e32 v142, v134
	v_mov_b32_e32 v143, v136
	v_mov_b32_e32 v144, v130
	v_mov_b32_e32 v145, v132
	global_store_dwordx4 v[138:139], v[142:145], off nt
	s_mov_b64 s[76:77], 0
	s_nop 0
	v_mov_b32_e32 v142, v135
	v_mov_b32_e32 v143, v137
	v_mov_b32_e32 v144, v131
	v_mov_b32_e32 v145, v133
	global_store_dwordx4 v[138:139], v[142:145], off offset:64 nt

.LBB0_522:
	global_store_dwordx4 v[138:139], v[134:137], off nt
	global_store_dwordx4 v[138:139], v[130:133], off offset:16 nt

.LBB0_535:
	v_mov_b64_e32 v[134:135], s[10:11]
	v_mad_i64_i32 v[134:135], s[34:35], v130, s93, v[134:135]
	v_cvt_pk_bf16_f32 v142, v126, v127
	v_cvt_pk_bf16_f32 v143, v128, v129
	v_cvt_pk_bf16_f32 v144, v122, v123
	v_cvt_pk_bf16_f32 v145, v124, v125
	v_lshl_add_u64 v[134:135], v[160:161], 1, v[134:135]
	s_and_b64 vcc, exec, s[6:7]
	v_subrev_u32_e32 v130, s13, v130
	flat_store_dwordx4 v[134:135], v[142:145]
	s_cbranch_vccnz .LBB0_546
	s_lshl_b32 s25, s12, 2
	s_add_i32 s34, s25, s74
	s_ashr_i32 s35, s34, 31
	s_mov_b64 s[76:77], -1
	s_mov_b64 s[56:57], 0
	s_cmp_lt_i32 s0, 9
	s_mov_b64 s[66:67], 0
	s_cbranch_scc1 .LBB0_542
	s_cmp_eq_u32 s0, 9
	s_mov_b64 s[66:67], -1
	s_cbranch_scc0 .LBB0_539
	s_lshl_b64 s[66:67], s[34:35], 18
	v_ashrrev_i32_e32 v131, 31, v130
	s_add_u32 s66, s48, s66
	s_addc_u32 s67, s49, s67
	v_lshlrev_b64 v[138:139], 10, v[130:131]
	v_and_b32_e32 v142, 0xffffffe0, v158
	v_lshl_add_u64 v[138:139], s[66:67], 0, v[138:139]
	v_ashrrev_i32_e32 v143, 31, v142
	v_lshl_add_u64 v[138:139], v[142:143], 2, v[138:139]
	v_lshlrev_b32_e32 v142, 2, v169
	v_mov_b32_e32 v143, v65
	v_lshl_add_u64 v[138:139], v[138:139], 0, v[142:143]
	v_mov_b32_e32 v142, v126
	v_mov_b32_e32 v143, v128
	v_mov_b32_e32 v144, v122
	v_mov_b32_e32 v145, v124
	global_store_dwordx4 v[138:139], v[142:145], off nt
	s_mov_b64 s[66:67], 0
	s_nop 0
	v_mov_b32_e32 v142, v127
	v_mov_b32_e32 v143, v129
	v_mov_b32_e32 v144, v123
	v_mov_b32_e32 v145, v125
	global_store_dwordx4 v[138:139], v[142:145], off offset:64 nt

.LBB0_541:
	s_lshl_b64 s[56:57], s[34:35], 18
	s_add_u32 s56, s69, s56
	s_addc_u32 s57, s62, s57
	v_lshlrev_b64 v[138:139], 10, v[130:131]
	v_lshl_add_u64 v[138:139], s[56:57], 0, v[138:139]
	v_ashrrev_i32_e32 v159, 31, v158
	v_lshl_add_u64 v[138:139], v[158:159], 2, v[138:139]
	global_store_dwordx4 v[138:139], v[126:129], off nt
	global_store_dwordx4 v[138:139], v[122:125], off offset:16 nt
	s_cbranch_execz .LBB0_545
	s_branch .LBB0_546

.LBB0_545:
	s_lshl_b64 s[34:35], s[34:35], 17
	s_add_u32 s34, s50, s34
	s_addc_u32 s35, s68, s35
	v_lshlrev_b64 v[138:139], 9, v[130:131]
	v_lshl_add_u64 v[138:139], s[34:35], 0, v[138:139]
	v_lshl_add_u64 v[138:139], v[164:165], 2, v[138:139]
	v_lshlrev_b32_e32 v142, 2, v181
	v_mov_b32_e32 v143, v65
	v_lshl_add_u64 v[138:139], v[138:139], 0, v[142:143]
	v_mov_b32_e32 v142, v126
	v_mov_b32_e32 v143, v128
	v_mov_b32_e32 v144, v122
	v_mov_b32_e32 v145, v124
	v_mov_b32_e32 v126, v127
	v_mov_b32_e32 v127, v129
	v_mov_b32_e32 v128, v123
	v_mov_b32_e32 v129, v125
	global_store_dwordx4 v[138:139], v[142:145], off nt
	global_store_dwordx4 v[138:139], v[126:129], off offset:128 nt

.LBB0_554:
	v_cvt_pk_bf16_f32 v122, v118, v119
	v_cvt_pk_bf16_f32 v123, v120, v121
	v_cvt_pk_bf16_f32 v124, v114, v115
	v_cvt_pk_bf16_f32 v125, v116, v117
	s_and_b64 vcc, exec, s[6:7]
	flat_store_dwordx4 v[134:135], v[122:125] offset:256
	s_cbranch_vccnz .LBB0_563
	s_lshl_b32 s25, s12, 2
	s_add_i32 s34, s25, s74
	s_ashr_i32 s35, s34, 31
	v_ashrrev_i32_e32 v131, 31, v130
	s_mov_b64 s[66:67], -1
	s_mov_b64 s[56:57], 0
	s_cmp_lt_i32 s0, 9
	s_mov_b64 s[76:77], 0
	s_cbranch_scc1 .LBB0_565
	s_cmp_eq_u32 s0, 9
	s_mov_b64 s[76:77], -1
	s_cbranch_scc0 .LBB0_558
	s_lshl_b64 s[66:67], s[34:35], 18
	s_add_u32 s66, s48, s66
	s_addc_u32 s67, s49, s67
	v_lshlrev_b64 v[122:123], 10, v[130:131]
	v_and_b32_e32 v124, 0xffffffe0, v140
	v_lshl_add_u64 v[122:123], s[66:67], 0, v[122:123]
	v_ashrrev_i32_e32 v125, 31, v124
	v_lshl_add_u64 v[122:123], v[124:125], 2, v[122:123]
	v_lshlrev_b32_e32 v64, 2, v169
	v_lshl_add_u64 v[126:127], v[122:123], 0, v[64:65]
	v_mov_b32_e32 v122, v118
	v_mov_b32_e32 v123, v120
	v_mov_b32_e32 v124, v114
	v_mov_b32_e32 v125, v116
	global_store_dwordx4 v[126:127], v[122:125], off nt
	s_mov_b64 s[76:77], 0
	s_nop 0
	v_mov_b32_e32 v122, v119
	v_mov_b32_e32 v123, v121
	v_mov_b32_e32 v124, v115
	v_mov_b32_e32 v125, v117
	global_store_dwordx4 v[126:127], v[122:125], off offset:64 nt

.LBB0_562:
	global_store_dwordx4 v[122:123], v[118:121], off nt
	global_store_dwordx4 v[122:123], v[114:117], off offset:16 nt

.LBB0_575:
	v_mov_b64_e32 v[118:119], s[10:11]
	v_mad_i64_i32 v[118:119], s[34:35], v114, s93, v[118:119]
	v_cvt_pk_bf16_f32 v122, v110, v111
	v_cvt_pk_bf16_f32 v123, v112, v113
	v_cvt_pk_bf16_f32 v124, v106, v107
	v_cvt_pk_bf16_f32 v125, v108, v109
	v_lshl_add_u64 v[118:119], v[160:161], 1, v[118:119]
	s_and_b64 vcc, exec, s[6:7]
	v_subrev_u32_e32 v114, s13, v114
	flat_store_dwordx4 v[118:119], v[122:125]
	s_cbranch_vccnz .LBB0_586
	s_lshl_b32 s25, s12, 2
	s_add_i32 s34, s25, s74
	s_ashr_i32 s35, s34, 31
	s_mov_b64 s[76:77], -1
	s_mov_b64 s[56:57], 0
	s_cmp_lt_i32 s0, 9
	s_mov_b64 s[66:67], 0
	s_cbranch_scc1 .LBB0_582
	s_cmp_eq_u32 s0, 9
	s_mov_b64 s[66:67], -1
	s_cbranch_scc0 .LBB0_579
	s_lshl_b64 s[66:67], s[34:35], 18
	v_ashrrev_i32_e32 v115, 31, v114
	s_add_u32 s66, s48, s66
	s_addc_u32 s67, s49, s67
	v_lshlrev_b64 v[122:123], 10, v[114:115]
	v_and_b32_e32 v124, 0xffffffe0, v158
	v_lshl_add_u64 v[122:123], s[66:67], 0, v[122:123]
	v_ashrrev_i32_e32 v125, 31, v124
	v_lshl_add_u64 v[122:123], v[124:125], 2, v[122:123]
	v_lshlrev_b32_e32 v124, 2, v169
	v_mov_b32_e32 v125, v65
	v_lshl_add_u64 v[126:127], v[122:123], 0, v[124:125]
	v_mov_b32_e32 v122, v110
	v_mov_b32_e32 v123, v112
	v_mov_b32_e32 v124, v106
	v_mov_b32_e32 v125, v108
	global_store_dwordx4 v[126:127], v[122:125], off nt
	s_mov_b64 s[66:67], 0
	s_nop 0
	v_mov_b32_e32 v122, v111
	v_mov_b32_e32 v123, v113
	v_mov_b32_e32 v124, v107
	v_mov_b32_e32 v125, v109
	global_store_dwordx4 v[126:127], v[122:125], off offset:64 nt

.LBB0_581:
	s_lshl_b64 s[56:57], s[34:35], 18
	s_add_u32 s56, s69, s56
	s_addc_u32 s57, s62, s57
	v_lshlrev_b64 v[122:123], 10, v[114:115]
	v_lshl_add_u64 v[122:123], s[56:57], 0, v[122:123]
	v_ashrrev_i32_e32 v159, 31, v158
	v_lshl_add_u64 v[122:123], v[158:159], 2, v[122:123]
	global_store_dwordx4 v[122:123], v[110:113], off nt
	global_store_dwordx4 v[122:123], v[106:109], off offset:16 nt
	s_cbranch_execz .LBB0_585
	s_branch .LBB0_586

.LBB0_585:
	s_lshl_b64 s[34:35], s[34:35], 17
	s_add_u32 s34, s50, s34
	s_addc_u32 s35, s68, s35
	v_lshlrev_b64 v[122:123], 9, v[114:115]
	v_lshl_add_u64 v[122:123], s[34:35], 0, v[122:123]
	v_lshl_add_u64 v[122:123], v[164:165], 2, v[122:123]
	v_lshlrev_b32_e32 v124, 2, v181
	v_mov_b32_e32 v125, v65
	v_lshl_add_u64 v[126:127], v[122:123], 0, v[124:125]
	v_mov_b32_e32 v122, v110
	v_mov_b32_e32 v123, v112
	v_mov_b32_e32 v124, v106
	v_mov_b32_e32 v125, v108
	v_mov_b32_e32 v110, v111
	v_mov_b32_e32 v111, v113
	v_mov_b32_e32 v112, v107
	v_mov_b32_e32 v113, v109
	global_store_dwordx4 v[126:127], v[122:125], off nt
	global_store_dwordx4 v[126:127], v[110:113], off offset:128 nt

.LBB0_594:
	v_cvt_pk_bf16_f32 v106, v102, v103
	v_cvt_pk_bf16_f32 v107, v104, v105
	v_cvt_pk_bf16_f32 v108, v98, v99
	v_cvt_pk_bf16_f32 v109, v100, v101
	s_and_b64 vcc, exec, s[6:7]
	flat_store_dwordx4 v[118:119], v[106:109] offset:256
	s_cbranch_vccnz .LBB0_603
	s_lshl_b32 s25, s12, 2
	s_add_i32 s34, s25, s74
	s_ashr_i32 s35, s34, 31
	v_ashrrev_i32_e32 v115, 31, v114
	s_mov_b64 s[66:67], -1
	s_mov_b64 s[56:57], 0
	s_cmp_lt_i32 s0, 9
	s_mov_b64 s[76:77], 0
	s_cbranch_scc1 .LBB0_605
	s_cmp_eq_u32 s0, 9
	s_mov_b64 s[76:77], -1
	s_cbranch_scc0 .LBB0_598
	s_lshl_b64 s[66:67], s[34:35], 18
	s_add_u32 s66, s48, s66
	s_addc_u32 s67, s49, s67
	v_lshlrev_b64 v[106:107], 10, v[114:115]
	v_and_b32_e32 v108, 0xffffffe0, v140
	v_lshl_add_u64 v[106:107], s[66:67], 0, v[106:107]
	v_ashrrev_i32_e32 v109, 31, v108
	v_lshl_add_u64 v[106:107], v[108:109], 2, v[106:107]
	v_lshlrev_b32_e32 v64, 2, v169
	v_lshl_add_u64 v[110:111], v[106:107], 0, v[64:65]
	v_mov_b32_e32 v106, v102
	v_mov_b32_e32 v107, v104
	v_mov_b32_e32 v108, v98
	v_mov_b32_e32 v109, v100
	global_store_dwordx4 v[110:111], v[106:109], off nt
	s_mov_b64 s[76:77], 0
	s_nop 0
	v_mov_b32_e32 v106, v103
	v_mov_b32_e32 v107, v105
	v_mov_b32_e32 v108, v99
	v_mov_b32_e32 v109, v101
	global_store_dwordx4 v[110:111], v[106:109], off offset:64 nt

.LBB0_602:
	global_store_dwordx4 v[106:107], v[102:105], off nt
	global_store_dwordx4 v[106:107], v[98:101], off offset:16 nt

.LBB0_615:
	v_mov_b64_e32 v[102:103], s[10:11]
	v_mad_i64_i32 v[102:103], s[34:35], v98, s93, v[102:103]
	v_cvt_pk_bf16_f32 v106, v94, v95
	v_cvt_pk_bf16_f32 v107, v96, v97
	v_cvt_pk_bf16_f32 v108, v90, v91
	v_cvt_pk_bf16_f32 v109, v92, v93
	v_lshl_add_u64 v[102:103], v[160:161], 1, v[102:103]
	s_and_b64 vcc, exec, s[6:7]
	v_subrev_u32_e32 v98, s13, v98
	flat_store_dwordx4 v[102:103], v[106:109]
	s_cbranch_vccnz .LBB0_626
	s_lshl_b32 s25, s12, 2
	s_add_i32 s34, s25, s74
	s_ashr_i32 s35, s34, 31
	s_mov_b64 s[76:77], -1
	s_mov_b64 s[56:57], 0
	s_cmp_lt_i32 s0, 9
	s_mov_b64 s[66:67], 0
	s_cbranch_scc1 .LBB0_622
	s_cmp_eq_u32 s0, 9
	s_mov_b64 s[66:67], -1
	s_cbranch_scc0 .LBB0_619
	s_lshl_b64 s[66:67], s[34:35], 18
	v_ashrrev_i32_e32 v99, 31, v98
	s_add_u32 s66, s48, s66
	s_addc_u32 s67, s49, s67
	v_lshlrev_b64 v[106:107], 10, v[98:99]
	v_and_b32_e32 v108, 0xffffffe0, v158
	v_lshl_add_u64 v[106:107], s[66:67], 0, v[106:107]
	v_ashrrev_i32_e32 v109, 31, v108
	v_lshl_add_u64 v[106:107], v[108:109], 2, v[106:107]
	v_lshlrev_b32_e32 v108, 2, v169
	v_mov_b32_e32 v109, v65
	v_lshl_add_u64 v[110:111], v[106:107], 0, v[108:109]
	v_mov_b32_e32 v106, v94
	v_mov_b32_e32 v107, v96
	v_mov_b32_e32 v108, v90
	v_mov_b32_e32 v109, v92
	global_store_dwordx4 v[110:111], v[106:109], off nt
	s_mov_b64 s[66:67], 0
	s_nop 0
	v_mov_b32_e32 v106, v95
	v_mov_b32_e32 v107, v97
	v_mov_b32_e32 v108, v91
	v_mov_b32_e32 v109, v93
	global_store_dwordx4 v[110:111], v[106:109], off offset:64 nt

.LBB0_621:
	s_lshl_b64 s[56:57], s[34:35], 18
	s_add_u32 s56, s69, s56
	s_addc_u32 s57, s62, s57
	v_lshlrev_b64 v[106:107], 10, v[98:99]
	v_lshl_add_u64 v[106:107], s[56:57], 0, v[106:107]
	v_ashrrev_i32_e32 v159, 31, v158
	v_lshl_add_u64 v[106:107], v[158:159], 2, v[106:107]
	global_store_dwordx4 v[106:107], v[94:97], off nt
	global_store_dwordx4 v[106:107], v[90:93], off offset:16 nt
	s_cbranch_execz .LBB0_625
	s_branch .LBB0_626

.LBB0_625:
	s_lshl_b64 s[34:35], s[34:35], 17
	s_add_u32 s34, s50, s34
	s_addc_u32 s35, s68, s35
	v_lshlrev_b64 v[106:107], 9, v[98:99]
	v_lshl_add_u64 v[106:107], s[34:35], 0, v[106:107]
	v_lshl_add_u64 v[106:107], v[164:165], 2, v[106:107]
	v_lshlrev_b32_e32 v108, 2, v181
	v_mov_b32_e32 v109, v65
	v_lshl_add_u64 v[110:111], v[106:107], 0, v[108:109]
	v_mov_b32_e32 v106, v94
	v_mov_b32_e32 v107, v96
	v_mov_b32_e32 v108, v90
	v_mov_b32_e32 v109, v92
	v_mov_b32_e32 v94, v95
	v_mov_b32_e32 v95, v97
	v_mov_b32_e32 v96, v91
	v_mov_b32_e32 v97, v93
	global_store_dwordx4 v[110:111], v[106:109], off nt
	global_store_dwordx4 v[110:111], v[94:97], off offset:128 nt

.LBB0_634:
	v_cvt_pk_bf16_f32 v90, v86, v87
	v_cvt_pk_bf16_f32 v91, v88, v89
	v_cvt_pk_bf16_f32 v92, v82, v83
	v_cvt_pk_bf16_f32 v93, v84, v85
	s_and_b64 vcc, exec, s[6:7]
	flat_store_dwordx4 v[102:103], v[90:93] offset:256
	s_cbranch_vccnz .LBB0_643
	s_lshl_b32 s25, s12, 2
	s_add_i32 s34, s25, s74
	s_ashr_i32 s35, s34, 31
	v_ashrrev_i32_e32 v99, 31, v98
	s_mov_b64 s[66:67], -1
	s_mov_b64 s[56:57], 0
	s_cmp_lt_i32 s0, 9
	s_mov_b64 s[76:77], 0
	s_cbranch_scc1 .LBB0_645
	s_cmp_eq_u32 s0, 9
	s_mov_b64 s[76:77], -1
	s_cbranch_scc0 .LBB0_638
	s_lshl_b64 s[66:67], s[34:35], 18
	s_add_u32 s66, s48, s66
	s_addc_u32 s67, s49, s67
	v_lshlrev_b64 v[90:91], 10, v[98:99]
	v_and_b32_e32 v92, 0xffffffe0, v140
	v_lshl_add_u64 v[90:91], s[66:67], 0, v[90:91]
	v_ashrrev_i32_e32 v93, 31, v92
	v_lshl_add_u64 v[90:91], v[92:93], 2, v[90:91]
	v_lshlrev_b32_e32 v64, 2, v169
	v_lshl_add_u64 v[94:95], v[90:91], 0, v[64:65]
	v_mov_b32_e32 v90, v86
	v_mov_b32_e32 v91, v88
	v_mov_b32_e32 v92, v82
	v_mov_b32_e32 v93, v84
	global_store_dwordx4 v[94:95], v[90:93], off nt
	s_mov_b64 s[76:77], 0
	s_nop 0
	v_mov_b32_e32 v90, v87
	v_mov_b32_e32 v91, v89
	v_mov_b32_e32 v92, v83
	v_mov_b32_e32 v93, v85
	global_store_dwordx4 v[94:95], v[90:93], off offset:64 nt

.LBB0_642:
	global_store_dwordx4 v[90:91], v[86:89], off nt
	global_store_dwordx4 v[90:91], v[82:85], off offset:16 nt

.LBB0_655:
	v_mov_b64_e32 v[86:87], s[10:11]
	v_mad_i64_i32 v[86:87], s[34:35], v82, s93, v[86:87]
	v_cvt_pk_bf16_f32 v90, v78, v79
	v_cvt_pk_bf16_f32 v91, v80, v81
	v_cvt_pk_bf16_f32 v92, v74, v75
	v_cvt_pk_bf16_f32 v93, v76, v77
	v_lshl_add_u64 v[86:87], v[160:161], 1, v[86:87]
	s_and_b64 vcc, exec, s[6:7]
	v_subrev_u32_e32 v82, s13, v82
	flat_store_dwordx4 v[86:87], v[90:93]
	s_cbranch_vccnz .LBB0_666
	s_lshl_b32 s25, s12, 2
	s_add_i32 s34, s25, s74
	s_ashr_i32 s35, s34, 31
	s_mov_b64 s[76:77], -1
	s_mov_b64 s[56:57], 0
	s_cmp_lt_i32 s0, 9
	s_mov_b64 s[66:67], 0
	s_cbranch_scc1 .LBB0_662
	s_cmp_eq_u32 s0, 9
	s_mov_b64 s[66:67], -1
	s_cbranch_scc0 .LBB0_659
	s_lshl_b64 s[66:67], s[34:35], 18
	v_ashrrev_i32_e32 v83, 31, v82
	s_add_u32 s66, s48, s66
	s_addc_u32 s67, s49, s67
	v_lshlrev_b64 v[90:91], 10, v[82:83]
	v_and_b32_e32 v92, 0xffffffe0, v158
	v_lshl_add_u64 v[90:91], s[66:67], 0, v[90:91]
	v_ashrrev_i32_e32 v93, 31, v92
	v_lshl_add_u64 v[90:91], v[92:93], 2, v[90:91]
	v_lshlrev_b32_e32 v92, 2, v169
	v_mov_b32_e32 v93, v65
	v_lshl_add_u64 v[94:95], v[90:91], 0, v[92:93]
	v_mov_b32_e32 v90, v78
	v_mov_b32_e32 v91, v80
	v_mov_b32_e32 v92, v74
	v_mov_b32_e32 v93, v76
	global_store_dwordx4 v[94:95], v[90:93], off nt
	s_mov_b64 s[66:67], 0
	s_nop 0
	v_mov_b32_e32 v90, v79
	v_mov_b32_e32 v91, v81
	v_mov_b32_e32 v92, v75
	v_mov_b32_e32 v93, v77
	global_store_dwordx4 v[94:95], v[90:93], off offset:64 nt

.LBB0_661:
	s_lshl_b64 s[56:57], s[34:35], 18
	s_add_u32 s56, s69, s56
	s_addc_u32 s57, s62, s57
	v_lshlrev_b64 v[90:91], 10, v[82:83]
	v_lshl_add_u64 v[90:91], s[56:57], 0, v[90:91]
	v_ashrrev_i32_e32 v159, 31, v158
	v_lshl_add_u64 v[90:91], v[158:159], 2, v[90:91]
	global_store_dwordx4 v[90:91], v[78:81], off nt
	global_store_dwordx4 v[90:91], v[74:77], off offset:16 nt
	s_cbranch_execz .LBB0_665
	s_branch .LBB0_666

.LBB0_665:
	s_lshl_b64 s[34:35], s[34:35], 17
	s_add_u32 s34, s50, s34
	s_addc_u32 s35, s68, s35
	v_lshlrev_b64 v[90:91], 9, v[82:83]
	v_lshl_add_u64 v[90:91], s[34:35], 0, v[90:91]
	v_lshl_add_u64 v[90:91], v[164:165], 2, v[90:91]
	v_lshlrev_b32_e32 v92, 2, v181
	v_mov_b32_e32 v93, v65
	v_lshl_add_u64 v[94:95], v[90:91], 0, v[92:93]
	v_mov_b32_e32 v90, v78
	v_mov_b32_e32 v91, v80
	v_mov_b32_e32 v92, v74
	v_mov_b32_e32 v93, v76
	v_mov_b32_e32 v78, v79
	v_mov_b32_e32 v79, v81
	v_mov_b32_e32 v80, v75
	v_mov_b32_e32 v81, v77
	global_store_dwordx4 v[94:95], v[90:93], off nt
	global_store_dwordx4 v[94:95], v[78:81], off offset:128 nt

.LBB0_674:
	v_cvt_pk_bf16_f32 v74, v70, v71
	v_cvt_pk_bf16_f32 v75, v72, v73
	v_cvt_pk_bf16_f32 v76, v66, v67
	v_cvt_pk_bf16_f32 v77, v68, v69
	s_and_b64 vcc, exec, s[6:7]
	flat_store_dwordx4 v[86:87], v[74:77] offset:256
	s_cbranch_vccnz .LBB0_683
	s_lshl_b32 s25, s12, 2
	s_add_i32 s34, s25, s74
	s_ashr_i32 s35, s34, 31
	v_ashrrev_i32_e32 v83, 31, v82
	s_mov_b64 s[66:67], -1
	s_mov_b64 s[56:57], 0
	s_cmp_lt_i32 s0, 9
	s_mov_b64 s[76:77], 0
	s_cbranch_scc1 .LBB0_685
	s_cmp_eq_u32 s0, 9
	s_mov_b64 s[76:77], -1
	s_cbranch_scc0 .LBB0_678
	s_lshl_b64 s[66:67], s[34:35], 18
	s_add_u32 s66, s48, s66
	s_addc_u32 s67, s49, s67
	v_lshlrev_b64 v[74:75], 10, v[82:83]
	v_and_b32_e32 v76, 0xffffffe0, v140
	v_lshl_add_u64 v[74:75], s[66:67], 0, v[74:75]
	v_ashrrev_i32_e32 v77, 31, v76
	v_lshl_add_u64 v[74:75], v[76:77], 2, v[74:75]
	v_lshlrev_b32_e32 v64, 2, v169
	v_lshl_add_u64 v[78:79], v[74:75], 0, v[64:65]
	v_mov_b32_e32 v74, v70
	v_mov_b32_e32 v75, v72
	v_mov_b32_e32 v76, v66
	v_mov_b32_e32 v77, v68
	global_store_dwordx4 v[78:79], v[74:77], off nt
	s_mov_b64 s[76:77], 0
	s_nop 0
	v_mov_b32_e32 v74, v71
	v_mov_b32_e32 v75, v73
	v_mov_b32_e32 v76, v67
	v_mov_b32_e32 v77, v69
	global_store_dwordx4 v[78:79], v[74:77], off offset:64 nt

.LBB0_682:
	global_store_dwordx4 v[74:75], v[70:73], off nt
	global_store_dwordx4 v[74:75], v[66:69], off offset:16 nt

.LBB0_695:
	v_mov_b64_e32 v[70:71], s[10:11]
	v_mad_i64_i32 v[70:71], s[34:35], v66, s93, v[70:71]
	v_cvt_pk_bf16_f32 v74, v60, v61
	v_cvt_pk_bf16_f32 v75, v62, v63
	v_cvt_pk_bf16_f32 v76, v56, v57
	v_cvt_pk_bf16_f32 v77, v58, v59
	v_lshl_add_u64 v[70:71], v[160:161], 1, v[70:71]
	s_and_b64 vcc, exec, s[6:7]
	v_subrev_u32_e32 v66, s13, v66
	flat_store_dwordx4 v[70:71], v[74:77]
	s_cbranch_vccnz .LBB0_706
	s_lshl_b32 s25, s12, 2
	s_add_i32 s34, s25, s74
	s_ashr_i32 s35, s34, 31
	s_mov_b64 s[76:77], -1
	s_mov_b64 s[56:57], 0
	s_cmp_lt_i32 s0, 9
	s_mov_b64 s[66:67], 0
	s_cbranch_scc1 .LBB0_702
	s_cmp_eq_u32 s0, 9
	s_mov_b64 s[66:67], -1
	s_cbranch_scc0 .LBB0_699
	s_lshl_b64 s[66:67], s[34:35], 18
	v_ashrrev_i32_e32 v67, 31, v66
	s_add_u32 s66, s48, s66
	s_addc_u32 s67, s49, s67
	v_lshlrev_b64 v[74:75], 10, v[66:67]
	v_and_b32_e32 v76, 0xffffffe0, v158
	v_lshl_add_u64 v[74:75], s[66:67], 0, v[74:75]
	v_ashrrev_i32_e32 v77, 31, v76
	v_lshl_add_u64 v[74:75], v[76:77], 2, v[74:75]
	v_lshlrev_b32_e32 v76, 2, v169
	v_mov_b32_e32 v77, v65
	v_lshl_add_u64 v[78:79], v[74:75], 0, v[76:77]
	v_mov_b32_e32 v74, v60
	v_mov_b32_e32 v75, v62
	v_mov_b32_e32 v76, v56
	v_mov_b32_e32 v77, v58
	global_store_dwordx4 v[78:79], v[74:77], off nt
	s_mov_b64 s[66:67], 0
	s_nop 0
	v_mov_b32_e32 v74, v61
	v_mov_b32_e32 v75, v63
	v_mov_b32_e32 v76, v57
	v_mov_b32_e32 v77, v59
	global_store_dwordx4 v[78:79], v[74:77], off offset:64 nt

.LBB0_701:
	s_lshl_b64 s[56:57], s[34:35], 18
	s_add_u32 s56, s69, s56
	s_addc_u32 s57, s62, s57
	v_lshlrev_b64 v[74:75], 10, v[66:67]
	v_lshl_add_u64 v[74:75], s[56:57], 0, v[74:75]
	v_ashrrev_i32_e32 v159, 31, v158
	v_lshl_add_u64 v[74:75], v[158:159], 2, v[74:75]
	global_store_dwordx4 v[74:75], v[60:63], off nt
	global_store_dwordx4 v[74:75], v[56:59], off offset:16 nt
	s_cbranch_execz .LBB0_705
	s_branch .LBB0_706

.LBB0_705:
	s_lshl_b64 s[34:35], s[34:35], 17
	s_add_u32 s34, s50, s34
	s_addc_u32 s35, s68, s35
	v_lshlrev_b64 v[74:75], 9, v[66:67]
	v_lshl_add_u64 v[74:75], s[34:35], 0, v[74:75]
	v_lshl_add_u64 v[74:75], v[164:165], 2, v[74:75]
	v_lshlrev_b32_e32 v76, 2, v181
	v_mov_b32_e32 v77, v65
	v_lshl_add_u64 v[78:79], v[74:75], 0, v[76:77]
	v_mov_b32_e32 v74, v60
	v_mov_b32_e32 v75, v62
	v_mov_b32_e32 v76, v56
	v_mov_b32_e32 v77, v58
	v_mov_b32_e32 v60, v61
	v_mov_b32_e32 v61, v63
	v_mov_b32_e32 v62, v57
	v_mov_b32_e32 v63, v59
	global_store_dwordx4 v[78:79], v[74:77], off nt
	global_store_dwordx4 v[78:79], v[60:63], off offset:128 nt

.LBB0_714:
	v_cvt_pk_bf16_f32 v56, v52, v53
	v_cvt_pk_bf16_f32 v57, v54, v55
	v_cvt_pk_bf16_f32 v58, v48, v49
	v_cvt_pk_bf16_f32 v59, v50, v51
	s_and_b64 vcc, exec, s[6:7]
	flat_store_dwordx4 v[70:71], v[56:59] offset:256
	s_cbranch_vccnz .LBB0_723
	s_lshl_b32 s25, s12, 2
	s_add_i32 s34, s25, s74
	s_ashr_i32 s35, s34, 31
	v_ashrrev_i32_e32 v67, 31, v66
	s_mov_b64 s[66:67], -1
	s_mov_b64 s[56:57], 0
	s_cmp_lt_i32 s0, 9
	s_mov_b64 s[76:77], 0
	s_cbranch_scc1 .LBB0_725
	s_cmp_eq_u32 s0, 9
	s_mov_b64 s[76:77], -1
	s_cbranch_scc0 .LBB0_718
	s_lshl_b64 s[66:67], s[34:35], 18
	s_add_u32 s66, s48, s66
	s_addc_u32 s67, s49, s67
	v_lshlrev_b64 v[56:57], 10, v[66:67]
	v_and_b32_e32 v58, 0xffffffe0, v140
	v_lshl_add_u64 v[56:57], s[66:67], 0, v[56:57]
	v_ashrrev_i32_e32 v59, 31, v58
	v_lshl_add_u64 v[56:57], v[58:59], 2, v[56:57]
	v_lshlrev_b32_e32 v64, 2, v169
	v_lshl_add_u64 v[60:61], v[56:57], 0, v[64:65]
	v_mov_b32_e32 v56, v52
	v_mov_b32_e32 v57, v54
	v_mov_b32_e32 v58, v48
	v_mov_b32_e32 v59, v50
	global_store_dwordx4 v[60:61], v[56:59], off nt
	s_mov_b64 s[76:77], 0
	s_nop 0
	v_mov_b32_e32 v56, v53
	v_mov_b32_e32 v57, v55
	v_mov_b32_e32 v58, v49
	v_mov_b32_e32 v59, v51
	global_store_dwordx4 v[60:61], v[56:59], off offset:64 nt

.LBB0_722:
	global_store_dwordx4 v[56:57], v[52:55], off nt
	global_store_dwordx4 v[56:57], v[48:51], off offset:16 nt

.LBB0_735:
	v_mov_b64_e32 v[52:53], s[10:11]
	v_mad_i64_i32 v[52:53], s[34:35], v48, s93, v[52:53]
	v_cvt_pk_bf16_f32 v56, v44, v45
	v_cvt_pk_bf16_f32 v57, v46, v47
	v_cvt_pk_bf16_f32 v58, v32, v33
	v_cvt_pk_bf16_f32 v59, v34, v35
	v_lshl_add_u64 v[52:53], v[160:161], 1, v[52:53]
	s_and_b64 vcc, exec, s[6:7]
	v_subrev_u32_e32 v48, s13, v48
	flat_store_dwordx4 v[52:53], v[56:59]
	s_cbranch_vccnz .LBB0_746
	s_lshl_b32 s25, s12, 2
	s_add_i32 s34, s25, s74
	s_ashr_i32 s35, s34, 31
	s_mov_b64 s[76:77], -1
	s_mov_b64 s[56:57], 0
	s_cmp_lt_i32 s0, 9
	s_mov_b64 s[66:67], 0
	s_cbranch_scc1 .LBB0_742
	s_cmp_eq_u32 s0, 9
	s_mov_b64 s[66:67], -1
	s_cbranch_scc0 .LBB0_739
	s_lshl_b64 s[66:67], s[34:35], 18
	v_ashrrev_i32_e32 v49, 31, v48
	s_add_u32 s66, s48, s66
	s_addc_u32 s67, s49, s67
	v_lshlrev_b64 v[56:57], 10, v[48:49]
	v_and_b32_e32 v58, 0xffffffe0, v158
	v_lshl_add_u64 v[56:57], s[66:67], 0, v[56:57]
	v_ashrrev_i32_e32 v59, 31, v58
	v_lshl_add_u64 v[56:57], v[58:59], 2, v[56:57]
	v_lshlrev_b32_e32 v58, 2, v169
	v_mov_b32_e32 v59, v65
	v_lshl_add_u64 v[60:61], v[56:57], 0, v[58:59]
	v_mov_b32_e32 v56, v44
	v_mov_b32_e32 v57, v46
	v_mov_b32_e32 v58, v32
	v_mov_b32_e32 v59, v34
	global_store_dwordx4 v[60:61], v[56:59], off nt
	s_mov_b64 s[66:67], 0
	s_nop 0
	v_mov_b32_e32 v56, v45
	v_mov_b32_e32 v57, v47
	v_mov_b32_e32 v58, v33
	v_mov_b32_e32 v59, v35
	global_store_dwordx4 v[60:61], v[56:59], off offset:64 nt

.LBB0_741:
	s_lshl_b64 s[56:57], s[34:35], 18
	s_add_u32 s56, s69, s56
	s_addc_u32 s57, s62, s57
	v_lshlrev_b64 v[56:57], 10, v[48:49]
	v_lshl_add_u64 v[56:57], s[56:57], 0, v[56:57]
	v_ashrrev_i32_e32 v159, 31, v158
	v_lshl_add_u64 v[56:57], v[158:159], 2, v[56:57]
	global_store_dwordx4 v[56:57], v[44:47], off nt
	global_store_dwordx4 v[56:57], v[32:35], off offset:16 nt
	s_cbranch_execz .LBB0_745
	s_branch .LBB0_746

.LBB0_745:
	s_lshl_b64 s[34:35], s[34:35], 17
	s_add_u32 s34, s50, s34
	s_addc_u32 s35, s68, s35
	v_lshlrev_b64 v[56:57], 9, v[48:49]
	v_lshl_add_u64 v[56:57], s[34:35], 0, v[56:57]
	v_lshl_add_u64 v[56:57], v[164:165], 2, v[56:57]
	v_lshlrev_b32_e32 v58, 2, v181
	v_mov_b32_e32 v59, v65
	v_lshl_add_u64 v[60:61], v[56:57], 0, v[58:59]
	v_mov_b32_e32 v56, v44
	v_mov_b32_e32 v57, v46
	v_mov_b32_e32 v58, v32
	v_mov_b32_e32 v59, v34
	v_mov_b32_e32 v44, v45
	v_mov_b32_e32 v45, v47
	v_mov_b32_e32 v46, v33
	v_mov_b32_e32 v47, v35
	global_store_dwordx4 v[60:61], v[56:59], off nt
	global_store_dwordx4 v[60:61], v[44:47], off offset:128 nt

.LBB0_754:
	v_cvt_pk_bf16_f32 v32, v20, v21
	v_cvt_pk_bf16_f32 v33, v22, v23
	v_cvt_pk_bf16_f32 v34, v16, v17
	v_cvt_pk_bf16_f32 v35, v18, v19
	s_and_b64 vcc, exec, s[6:7]
	flat_store_dwordx4 v[52:53], v[32:35] offset:256
	s_cbranch_vccnz .LBB0_763
	s_lshl_b32 s25, s12, 2
	s_add_i32 s34, s25, s74
	s_ashr_i32 s35, s34, 31
	v_ashrrev_i32_e32 v49, 31, v48
	s_mov_b64 s[66:67], -1
	s_mov_b64 s[56:57], 0
	s_cmp_lt_i32 s0, 9
	s_mov_b64 s[76:77], 0
	s_cbranch_scc1 .LBB0_765
	s_cmp_eq_u32 s0, 9
	s_mov_b64 s[76:77], -1
	s_cbranch_scc0 .LBB0_758
	s_lshl_b64 s[66:67], s[34:35], 18
	s_add_u32 s66, s48, s66
	s_addc_u32 s67, s49, s67
	v_lshlrev_b64 v[32:33], 10, v[48:49]
	v_and_b32_e32 v34, 0xffffffe0, v140
	v_lshl_add_u64 v[32:33], s[66:67], 0, v[32:33]
	v_ashrrev_i32_e32 v35, 31, v34
	v_lshl_add_u64 v[32:33], v[34:35], 2, v[32:33]
	v_lshlrev_b32_e32 v64, 2, v169
	v_lshl_add_u64 v[44:45], v[32:33], 0, v[64:65]
	v_mov_b32_e32 v32, v20
	v_mov_b32_e32 v33, v22
	v_mov_b32_e32 v34, v16
	v_mov_b32_e32 v35, v18
	global_store_dwordx4 v[44:45], v[32:35], off nt
	s_mov_b64 s[76:77], 0
	s_nop 0
	v_mov_b32_e32 v32, v21
	v_mov_b32_e32 v33, v23
	v_mov_b32_e32 v34, v17
	v_mov_b32_e32 v35, v19
	global_store_dwordx4 v[44:45], v[32:35], off offset:64 nt

.LBB0_762:
	global_store_dwordx4 v[32:33], v[20:23], off nt
	global_store_dwordx4 v[32:33], v[16:19], off offset:16 nt

.LBB0_775:
	v_mov_b64_e32 v[20:21], s[10:11]
	v_mad_i64_i32 v[20:21], s[34:35], v16, s93, v[20:21]
	v_cvt_pk_bf16_f32 v32, v12, v13
	v_cvt_pk_bf16_f32 v33, v14, v15
	v_cvt_pk_bf16_f32 v34, v8, v9
	v_cvt_pk_bf16_f32 v35, v10, v11
	v_lshl_add_u64 v[20:21], v[160:161], 1, v[20:21]
	s_and_b64 vcc, exec, s[6:7]
	v_subrev_u32_e32 v16, s13, v16
	flat_store_dwordx4 v[20:21], v[32:35]
	s_cbranch_vccnz .LBB0_786
	s_lshl_b32 s13, s12, 2
	s_add_i32 s34, s13, s74
	s_ashr_i32 s35, s34, 31
	s_mov_b64 s[76:77], -1
	s_mov_b64 s[56:57], 0
	s_cmp_lt_i32 s0, 9
	s_mov_b64 s[66:67], 0
	s_cbranch_scc1 .LBB0_782
	s_cmp_eq_u32 s0, 9
	s_mov_b64 s[66:67], -1
	s_cbranch_scc0 .LBB0_779
	s_lshl_b64 s[66:67], s[34:35], 18
	v_ashrrev_i32_e32 v17, 31, v16
	s_add_u32 s66, s48, s66
	s_addc_u32 s67, s49, s67
	v_lshlrev_b64 v[32:33], 10, v[16:17]
	v_and_b32_e32 v34, 0xffffffe0, v158
	v_lshl_add_u64 v[32:33], s[66:67], 0, v[32:33]
	v_ashrrev_i32_e32 v35, 31, v34
	v_lshl_add_u64 v[32:33], v[34:35], 2, v[32:33]
	v_lshlrev_b32_e32 v34, 2, v169
	v_mov_b32_e32 v35, v65
	v_lshl_add_u64 v[36:37], v[32:33], 0, v[34:35]
	v_mov_b32_e32 v32, v12
	v_mov_b32_e32 v33, v14
	v_mov_b32_e32 v34, v8
	v_mov_b32_e32 v35, v10
	global_store_dwordx4 v[36:37], v[32:35], off nt
	s_mov_b64 s[66:67], 0
	s_nop 0
	v_mov_b32_e32 v32, v13
	v_mov_b32_e32 v33, v15
	v_mov_b32_e32 v34, v9
	v_mov_b32_e32 v35, v11
	global_store_dwordx4 v[36:37], v[32:35], off offset:64 nt

.LBB0_781:
	s_lshl_b64 s[56:57], s[34:35], 18
	s_add_u32 s56, s69, s56
	s_addc_u32 s57, s62, s57
	v_lshlrev_b64 v[32:33], 10, v[16:17]
	v_lshl_add_u64 v[32:33], s[56:57], 0, v[32:33]
	v_ashrrev_i32_e32 v159, 31, v158
	v_lshl_add_u64 v[32:33], v[158:159], 2, v[32:33]
	global_store_dwordx4 v[32:33], v[12:15], off nt
	global_store_dwordx4 v[32:33], v[8:11], off offset:16 nt
	s_cbranch_execz .LBB0_785
	s_branch .LBB0_786

.LBB0_785:
	s_lshl_b64 s[34:35], s[34:35], 17
	s_add_u32 s34, s50, s34
	s_addc_u32 s35, s68, s35
	v_lshlrev_b64 v[32:33], 9, v[16:17]
	v_lshl_add_u64 v[32:33], s[34:35], 0, v[32:33]
	v_lshl_add_u64 v[32:33], v[164:165], 2, v[32:33]
	v_lshlrev_b32_e32 v34, 2, v181
	v_mov_b32_e32 v35, v65
	v_lshl_add_u64 v[36:37], v[32:33], 0, v[34:35]
	v_mov_b32_e32 v32, v12
	v_mov_b32_e32 v33, v14
	v_mov_b32_e32 v34, v8
	v_mov_b32_e32 v35, v10
	v_mov_b32_e32 v12, v13
	v_mov_b32_e32 v13, v15
	v_mov_b32_e32 v14, v9
	v_mov_b32_e32 v15, v11
	global_store_dwordx4 v[36:37], v[32:35], off nt
	global_store_dwordx4 v[36:37], v[12:15], off offset:128 nt

.LBB0_794:
	v_cvt_pk_bf16_f32 v8, v4, v5
	v_cvt_pk_bf16_f32 v9, v6, v7
	v_cvt_pk_bf16_f32 v10, v0, v1
	v_cvt_pk_bf16_f32 v11, v2, v3
	s_and_b64 vcc, exec, s[6:7]
	flat_store_dwordx4 v[20:21], v[8:11] offset:256
	s_cbranch_vccnz .LBB0_805
	s_lshl_b32 s1, s12, 2
	s_add_i32 s6, s1, s74
	s_ashr_i32 s7, s6, 31
	v_ashrrev_i32_e32 v17, 31, v16
	s_mov_b64 s[56:57], -1
	s_mov_b64 s[12:13], 0
	s_cmp_lt_i32 s0, 9
	s_mov_b64 s[34:35], 0
	s_cbranch_scc1 .LBB0_799
	s_cmp_eq_u32 s0, 9
	s_mov_b64 s[34:35], -1
	s_cbranch_scc0 .LBB0_798
	s_lshl_b64 s[34:35], s[6:7], 18
	s_add_u32 s34, s48, s34
	s_addc_u32 s35, s49, s35
	v_lshlrev_b64 v[8:9], 10, v[16:17]
	v_and_b32_e32 v10, 0xffffffe0, v140
	v_lshl_add_u64 v[8:9], s[34:35], 0, v[8:9]
	v_ashrrev_i32_e32 v11, 31, v10
	v_lshl_add_u64 v[8:9], v[10:11], 2, v[8:9]
	v_lshlrev_b32_e32 v64, 2, v169
	v_lshl_add_u64 v[12:13], v[8:9], 0, v[64:65]
	v_mov_b32_e32 v8, v4
	v_mov_b32_e32 v9, v6
	v_mov_b32_e32 v10, v0
	v_mov_b32_e32 v11, v2
	global_store_dwordx4 v[12:13], v[8:11], off nt
	s_mov_b64 s[34:35], 0
	s_nop 0
	v_mov_b32_e32 v8, v5
	v_mov_b32_e32 v9, v7
	v_mov_b32_e32 v10, v1
	v_mov_b32_e32 v11, v3
	global_store_dwordx4 v[12:13], v[8:11], off offset:64 nt

.LBB0_804:
	global_store_dwordx4 v[8:9], v[4:7], off nt
	global_store_dwordx4 v[8:9], v[0:3], off offset:16 nt
